# hand-written neighbourhood-attention phase (lean softmax, Q fragments in registers, masked bias table, cross-unit prefetch, packed epilogue) on top of the retention edits
# speedup vs baseline: 1.0315x; 1.0315x over previous
.LBB0_227:
	s_or_b64 exec, exec, s[6:7]
	s_lshr_b32 s10, s22, 1
	s_mov_b64 s[6:7], -1
	s_and_b64 vcc, exec, s[4:5]
	s_waitcnt lgkmcnt(0)
	s_barrier
	s_cbranch_vccz .LBB0_331
	s_movk_i32 s41, 0x480
	s_cmp_eq_u32 s22, 3
	s_cselect_b32 s41, 0x400, s41
	s_mov_b32 s53, 0x3e0293ee
	v_readlane_b32 s24, v253, 8
	v_readlane_b32 s25, v253, 9
	s_mul_i32 s1, s10, 0xe880
	s_add_u32 s24, s24, s1
	s_addc_u32 s25, s25, 0
	s_add_u32 s26, s92, 0x18e00000
	s_addc_u32 s27, s93, 0
	s_add_u32 s28, s92, 0x2ae00000
	s_addc_u32 s29, s93, 0
	v_readfirstlane_b32 s36, v172
	s_lshr_b32 s36, s36, 6
	s_and_b32 s37, s36, 3
	s_lshr_b32 s38, s36, 2
	s_lshl_b32 s39, s37, 3
	s_cmp_gt_u32 s37, 1
	s_cselect_b32 s1, 8, 0
	s_add_u32 s39, s39, s1
	v_and_b32_e32 v192, 15, v246
	v_lshrrev_b32_e32 v193, 4, v246
	v_lshrrev_b32_e32 v224, 4, v172
	v_and_b32_e32 v225, 15, v172
	v_lshlrev_b32_e32 v194, 15, v224
	v_lshl_add_u32 v194, v225, 4, v194
	v_add_u32_e32 v195, 0x100000, v194
	v_mul_u32_u24_e32 v196, 0x110, v224
	v_lshl_add_u32 v196, v225, 4, v196
	v_mul_u32_u24_e32 v197, 0x120, v224
	v_lshl_add_u32 v197, v225, 4, v197
	v_add_u32_e32 v197, 0x4400, v197
	v_mul_u32_u24_e32 v199, 0x110, v192
	v_lshl_add_u32 v199, v193, 4, v199
	s_mul_i32 s1, s39, 0x110
	v_add_u32_e32 v198, s1, v199
	v_lshrrev_b32_e32 v224, 2, v192
	v_lshl_add_u32 v224, v193, 2, v224
	v_mul_u32_u24_e32 v201, 0x120, v224
	v_and_b32_e32 v225, 3, v192
	v_lshl_add_u32 v201, v225, 3, v201
	v_add_u32_e32 v201, 0x4400, v201
	s_mul_i32 s1, s39, 0x120
	v_add_u32_e32 v200, s1, v201
	v_lshl_add_u32 v228, s37, 4, v192
	v_add_u32_e32 v224, -8, v228
	v_max_i32_e32 v224, 0, v224
	v_min_i32_e32 v229, 48, v224
	v_lshl_add_u32 v230, v193, 2, s39
	v_add_u32_e32 v224, 0, v230
	v_sub_u32_e32 v225, v224, v229
	v_cmp_gt_u32_e32 vcc, 16, v225
	v_sub_u32_e32 v224, v224, v228
	v_add_u32_e32 v224, 15, v224
	v_cndmask_b32_e32 v224, 31, v224, vcc
	v_lshlrev_b32_e32 v202, 2, v224
	v_add_u32_e32 v224, 1, v230
	v_sub_u32_e32 v225, v224, v229
	v_cmp_gt_u32_e32 vcc, 16, v225
	v_sub_u32_e32 v224, v224, v228
	v_add_u32_e32 v224, 15, v224
	v_cndmask_b32_e32 v224, 31, v224, vcc
	v_lshlrev_b32_e32 v203, 2, v224
	v_add_u32_e32 v224, 2, v230
	v_sub_u32_e32 v225, v224, v229
	v_cmp_gt_u32_e32 vcc, 16, v225
	v_sub_u32_e32 v224, v224, v228
	v_add_u32_e32 v224, 15, v224
	v_cndmask_b32_e32 v224, 31, v224, vcc
	v_lshlrev_b32_e32 v204, 2, v224
	v_add_u32_e32 v224, 3, v230
	v_sub_u32_e32 v225, v224, v229
	v_cmp_gt_u32_e32 vcc, 16, v225
	v_sub_u32_e32 v224, v224, v228
	v_add_u32_e32 v224, 15, v224
	v_cndmask_b32_e32 v224, 31, v224, vcc
	v_lshlrev_b32_e32 v205, 2, v224
	v_add_u32_e32 v224, 16, v230
	v_sub_u32_e32 v225, v224, v229
	v_cmp_gt_u32_e32 vcc, 16, v225
	v_sub_u32_e32 v224, v224, v228
	v_add_u32_e32 v224, 15, v224
	v_cndmask_b32_e32 v224, 31, v224, vcc
	v_lshlrev_b32_e32 v206, 2, v224
	v_add_u32_e32 v224, 17, v230
	v_sub_u32_e32 v225, v224, v229
	v_cmp_gt_u32_e32 vcc, 16, v225
	v_sub_u32_e32 v224, v224, v228
	v_add_u32_e32 v224, 15, v224
	v_cndmask_b32_e32 v224, 31, v224, vcc
	v_lshlrev_b32_e32 v207, 2, v224
	v_add_u32_e32 v224, 18, v230
	v_sub_u32_e32 v225, v224, v229
	v_cmp_gt_u32_e32 vcc, 16, v225
	v_sub_u32_e32 v224, v224, v228
	v_add_u32_e32 v224, 15, v224
	v_cndmask_b32_e32 v224, 31, v224, vcc
	v_lshlrev_b32_e32 v208, 2, v224
	v_add_u32_e32 v224, 19, v230
	v_sub_u32_e32 v225, v224, v229
	v_cmp_gt_u32_e32 vcc, 16, v225
	v_sub_u32_e32 v224, v224, v228
	v_add_u32_e32 v224, 15, v224
	v_cndmask_b32_e32 v224, 31, v224, vcc
	v_lshlrev_b32_e32 v209, 2, v224
	v_lshlrev_b32_e32 v210, 15, v192
	v_lshl_add_u32 v210, v193, 4, v210
	v_lshlrev_b32_e32 v211, 15, v192
	v_lshl_add_u32 v211, v193, 3, v211
	v_lshlrev_b32_e32 v212, 13, v192
	v_lshl_add_u32 v212, v193, 3, v212
	v_lshrrev_b32_e32 v224, 5, v172
	v_and_b32_e32 v225, 31, v172
	v_cmp_gt_u32_e32 vcc, 15, v224
	v_cmp_gt_u32_e64 s[22:23], 31, v225
	s_and_b64 s[22:23], s[22:23], vcc
	v_mul_u32_u24_e32 v224, 31, v224
	v_add_lshl_u32 v224, v224, v225, 2
	v_cndmask_b32_e64 v213, 0, v224, s[22:23]
	v_lshlrev_b32_e32 v214, 2, v172
	v_add_u32_e32 v214, 0x11800, v214
	v_xor_b32_e32 v215, 16, v246
	v_lshlrev_b32_e32 v215, 2, v215
	v_xor_b32_e32 v216, 32, v246
	v_lshlrev_b32_e32 v216, 2, v216
	v_xor_b32_e32 v217, 48, v246
	v_lshlrev_b32_e32 v217, 2, v217
	s_mov_b32 s40, s62
	s_cmp_ge_u32 s40, 0x400
	s_cbranch_scc1 .Lna_dec_ctx_0
	s_mov_b32 s45, 0
	s_cmp_eq_u32 s94, 0x100
	s_cbranch_scc0 .Lna_dec_gen_0
	s_lshr_b32 s1, s40, 8
	s_and_b32 s2, s40, 0xff
	s_lshl_b32 s1, s1, 5
	s_and_b32 s4, s2, 7
	s_lshl_b32 s4, s4, 2
	s_add_u32 s1, s1, s4
	s_lshr_b32 s4, s2, 6
	s_add_u32 s1, s1, s4
	s_bfe_u32 s44, s2, 0x30003
	s_branch .Lna_dec_l2_0
.Lna_dec_gen_0:
	s_lshr_b32 s1, s40, 3
	s_and_b32 s44, s40, 7
.Lna_dec_l2_0:
	s_lshr_b32 s42, s1, 5
	s_and_b32 s43, s1, 31
	s_lshl_b32 s1, s44, 2
	s_lshl_b32 s2, s38, 1
	s_add_u32 s46, s1, s2
	s_lshl_b32 s4, s42, 11
	s_lshl_b32 s5, s46, 6
	s_add_u32 s4, s4, s5
	s_lshl_b32 s5, s37, 4
	s_add_u32 s4, s4, s5
	s_add_u32 s5, s4, 64
	s_sub_i32 s6, s46, 4
	s_max_i32 s6, s6, 0
	s_min_i32 s47, s6, 24
	s_sub_i32 s6, s46, 3
	s_max_i32 s6, s6, 0
	s_min_i32 s48, s6, 24
	s_sub_i32 s6, s1, 4
	s_max_i32 s6, s6, 0
	s_min_i32 s49, s6, 24
	s_sub_i32 s6, s1, 1
	s_max_i32 s6, s6, 0
	s_min_i32 s6, s6, 24
	s_add_u32 s6, s6, 8
	s_sub_u32 s50, s6, s49
	s_branch .Lna_dec_done_0
.Lna_dec_ctx_0:
	s_mov_b32 s45, 1
	s_sub_u32 s1, s40, 0x400
	s_lshr_b32 s42, s1, 5
	s_and_b32 s43, s1, 31
	s_lshl_b32 s4, s42, 8
	s_add_u32 s4, s4, 0x2000
	s_lshl_b32 s5, s36, 4
	s_add_u32 s4, s4, s5
	s_add_u32 s5, s4, 0x80
	s_mov_b32 s50, 0
	s_mov_b32 s49, 0
	s_mov_b32 s46, 0
	s_mov_b32 s47, 0
	s_mov_b32 s48, 0
.Lna_dec_done_0:
	s_add_u32 s51, s50, 4
	s_mov_b32 s8, s4
	s_mov_b32 s9, s5
	s_lshl_b32 s6, s43, 8
	s_lshl_b32 s7, s4, 15
	s_add_u32 s7, s7, s6
	s_add_u32 s58, s26, s7
	s_addc_u32 s59, s27, 0
	s_lshl_b32 s7, s5, 15
	s_add_u32 s7, s7, s6
	s_add_u32 s60, s26, s7
	s_addc_u32 s61, s27, 0
	s_mul_i32 s7, s43, 0x744
	s_add_u32 s64, s24, s7
	s_addc_u32 s65, s25, 0
	global_load_dwordx4 v[64:67], v210, s[58:59]
	global_load_dwordx4 v[68:71], v210, s[58:59] offset:64
	global_load_dwordx4 v[72:75], v210, s[58:59] offset:128
	global_load_dwordx4 v[76:79], v210, s[58:59] offset:192
	global_load_dwordx4 v[80:83], v210, s[60:61]
	global_load_dwordx4 v[84:87], v210, s[60:61] offset:64
	global_load_dwordx4 v[88:91], v210, s[60:61] offset:128
	global_load_dwordx4 v[92:95], v210, s[60:61] offset:192
	global_load_dword v236, v213, s[64:65]
	s_mov_b32 s52, 0
	s_cmp_lt_u32 s52, s50
	s_cbranch_scc0 .Lna_tb_ctx0
	s_add_u32 s1, s49, s52
	s_lshl_b32 s1, s1, 6
	s_lshl_b32 s2, s42, 11
	s_add_u32 s1, s1, s2
	s_branch .Lna_tb_done0
.Lna_tb_ctx0:
	s_sub_u32 s1, s52, s50
	s_lshl_b32 s1, s1, 6
	s_lshl_b32 s2, s42, 8
	s_add_u32 s1, s1, s2
	s_add_u32 s1, s1, 0x2000
.Lna_tb_done0:
	s_lshl_b32 s1, s1, 15
	s_lshl_b32 s2, s43, 8
	s_add_u32 s1, s1, s2
	s_add_u32 s1, s1, 0x2000
	s_add_u32 s54, s26, s1
	s_addc_u32 s55, s27, 0
	s_add_u32 s56, s54, 0x2000
	s_addc_u32 s57, s55, 0
	global_load_dwordx4 v[96:99], v194, s[54:55]
	global_load_dwordx4 v[100:103], v194, s[56:57]
	global_load_dwordx4 v[104:107], v195, s[54:55]
	global_load_dwordx4 v[108:111], v195, s[56:57]
	s_mov_b32 s11, 1
	s_cmp_lt_u32 s11, s50
	s_cbranch_scc0 .Lna_tb_ctx1
	s_add_u32 s1, s49, s11
	s_lshl_b32 s1, s1, 6
	s_lshl_b32 s2, s42, 11
	s_add_u32 s1, s1, s2
	s_branch .Lna_tb_done1
.Lna_tb_ctx1:
	s_sub_u32 s1, s11, s50
	s_lshl_b32 s1, s1, 6
	s_lshl_b32 s2, s42, 8
	s_add_u32 s1, s1, s2
	s_add_u32 s1, s1, 0x2000
.Lna_tb_done1:
	s_lshl_b32 s1, s1, 15
	s_lshl_b32 s2, s43, 8
	s_add_u32 s1, s1, s2
	s_add_u32 s1, s1, 0x2000
	s_add_u32 s54, s26, s1
	s_addc_u32 s55, s27, 0
	s_add_u32 s56, s54, 0x2000
	s_addc_u32 s57, s55, 0
	global_load_dwordx4 v[128:131], v194, s[54:55]
	global_load_dwordx4 v[132:135], v194, s[56:57]
	global_load_dwordx4 v[136:139], v195, s[54:55]
	global_load_dwordx4 v[140:143], v195, s[56:57]
	v_mov_b64_e32 v[0:1], 0
	v_mov_b64_e32 v[2:3], 0
	v_mov_b64_e32 v[4:5], 0
	v_mov_b64_e32 v[6:7], 0
	v_mov_b64_e32 v[8:9], 0
	v_mov_b64_e32 v[10:11], 0
	v_mov_b64_e32 v[12:13], 0
	v_mov_b64_e32 v[14:15], 0
	v_mov_b64_e32 v[16:17], 0
	v_mov_b64_e32 v[18:19], 0
	v_mov_b64_e32 v[20:21], 0
	v_mov_b64_e32 v[22:23], 0
	v_mov_b64_e32 v[24:25], 0
	v_mov_b64_e32 v[26:27], 0
	v_mov_b64_e32 v[28:29], 0
	v_mov_b64_e32 v[30:31], 0
	v_mov_b64_e32 v[32:33], 0
	v_mov_b64_e32 v[34:35], 0
	v_mov_b64_e32 v[36:37], 0
	v_mov_b64_e32 v[38:39], 0
	v_mov_b64_e32 v[40:41], 0
	v_mov_b64_e32 v[42:43], 0
	v_mov_b64_e32 v[44:45], 0
	v_mov_b64_e32 v[46:47], 0
	v_mov_b64_e32 v[48:49], 0
	v_mov_b64_e32 v[50:51], 0
	v_mov_b64_e32 v[52:53], 0
	v_mov_b64_e32 v[54:55], 0
	v_mov_b64_e32 v[56:57], 0
	v_mov_b64_e32 v[58:59], 0
	v_mov_b64_e32 v[60:61], 0
	v_mov_b64_e32 v[62:63], 0
	v_mov_b32_e32 v218, 0xf149f2ca
	v_mov_b32_e32 v221, 0xf149f2ca
	v_mov_b32_e32 v219, 0xf149f2ca
	v_mov_b32_e32 v222, 0xf149f2ca
	v_mov_b32_e32 v220, 0
	v_mov_b32_e32 v223, 0
	s_waitcnt vmcnt(8)
	v_mul_f32_e32 v236, 0x3fb8aa3b, v236
	v_cndmask_b32_e64 v236, v247, v236, s[22:23]
	ds_write_b32 v214, v236
	s_waitcnt vmcnt(4)
	v_mov_b32_e32 v234, v196
	v_mov_b32_e32 v235, v197
	ds_write_b128 v234, v[96:99]
	ds_write_b128 v235, v[100:103]
	ds_write_b128 v234, v[104:107] offset:8704
	ds_write_b128 v235, v[108:111] offset:9216
	s_waitcnt lgkmcnt(0)
	s_barrier
	s_branch .Lna_itloop
.Lna_unit_next:
	v_mov_b64_e32 v[0:1], 0
	v_mov_b64_e32 v[2:3], 0
	v_mov_b64_e32 v[4:5], 0
	v_mov_b64_e32 v[6:7], 0
	v_mov_b64_e32 v[8:9], 0
	v_mov_b64_e32 v[10:11], 0
	v_mov_b64_e32 v[12:13], 0
	v_mov_b64_e32 v[14:15], 0
	v_mov_b64_e32 v[16:17], 0
	v_mov_b64_e32 v[18:19], 0
	v_mov_b64_e32 v[20:21], 0
	v_mov_b64_e32 v[22:23], 0
	v_mov_b64_e32 v[24:25], 0
	v_mov_b64_e32 v[26:27], 0
	v_mov_b64_e32 v[28:29], 0
	v_mov_b64_e32 v[30:31], 0
	v_mov_b64_e32 v[32:33], 0
	v_mov_b64_e32 v[34:35], 0
	v_mov_b64_e32 v[36:37], 0
	v_mov_b64_e32 v[38:39], 0
	v_mov_b64_e32 v[40:41], 0
	v_mov_b64_e32 v[42:43], 0
	v_mov_b64_e32 v[44:45], 0
	v_mov_b64_e32 v[46:47], 0
	v_mov_b64_e32 v[48:49], 0
	v_mov_b64_e32 v[50:51], 0
	v_mov_b64_e32 v[52:53], 0
	v_mov_b64_e32 v[54:55], 0
	v_mov_b64_e32 v[56:57], 0
	v_mov_b64_e32 v[58:59], 0
	v_mov_b64_e32 v[60:61], 0
	v_mov_b64_e32 v[62:63], 0
	v_mov_b32_e32 v218, 0xf149f2ca
	v_mov_b32_e32 v221, 0xf149f2ca
	v_mov_b32_e32 v219, 0xf149f2ca
	v_mov_b32_e32 v222, 0xf149f2ca
	v_mov_b32_e32 v220, 0
	v_mov_b32_e32 v223, 0
	s_waitcnt vmcnt(24)
	v_mul_f32_e32 v236, 0x3fb8aa3b, v236
	v_cndmask_b32_e64 v236, v247, v236, s[22:23]
	ds_write_b32 v214, v236
	s_waitcnt vmcnt(20)
	v_mov_b32_e32 v234, v196
	v_mov_b32_e32 v235, v197
	ds_write_b128 v234, v[96:99]
	ds_write_b128 v235, v[100:103]
	ds_write_b128 v234, v[104:107] offset:8704
	ds_write_b128 v235, v[108:111] offset:9216
	s_waitcnt lgkmcnt(0)
	s_barrier
.Lna_itloop:
	s_mov_b32 s52, 0
	s_mov_b32 s66, 0
.Lna_it:
	s_add_u32 s11, s52, 1
	s_cmp_lt_u32 s11, s51
	s_cselect_b32 s67, 1, 0
	s_add_u32 s11, s52, 2
	s_cmp_lt_u32 s11, s51
	s_cselect_b32 s14, 1, 0
	s_cbranch_scc0 .Lna_noload
	s_cmp_lt_u32 s11, s50
	s_cbranch_scc0 .Lna_tb_ctx2
	s_add_u32 s1, s49, s11
	s_lshl_b32 s1, s1, 6
	s_lshl_b32 s2, s42, 11
	s_add_u32 s1, s1, s2
	s_branch .Lna_tb_done2

.Lna_tb_done2:
	s_lshl_b32 s1, s1, 15
	s_lshl_b32 s2, s43, 8
	s_add_u32 s1, s1, s2
	s_add_u32 s1, s1, 0x2000
	s_add_u32 s54, s26, s1
	s_addc_u32 s55, s27, 0
	s_add_u32 s56, s54, 0x2000
	s_addc_u32 s57, s55, 0
	s_bitcmp1_b32 s52, 0
	s_cbranch_scc1 .Lna_ld_odd
	global_load_dwordx4 v[96:99], v194, s[54:55]
	global_load_dwordx4 v[100:103], v194, s[56:57]
	global_load_dwordx4 v[104:107], v195, s[54:55]
	global_load_dwordx4 v[108:111], v195, s[56:57]
	s_branch .Lna_noload
.Lna_ld_odd:
	global_load_dwordx4 v[128:131], v194, s[54:55]
	global_load_dwordx4 v[132:135], v194, s[56:57]
	global_load_dwordx4 v[136:139], v195, s[54:55]
	global_load_dwordx4 v[140:143], v195, s[56:57]
.Lna_noload:
	s_cmp_lt_u32 s52, s50
	s_cbranch_scc0 .Lna_ctx
	s_add_u32 s1, s49, s52
	s_sub_u32 s2, s1, s47
	s_cmp_lt_u32 s2, 8
	s_cselect_b32 s4, 1, 0
	s_sub_u32 s2, s1, s48
	s_cmp_lt_u32 s2, 8
	s_cselect_b32 s5, 1, 0
	s_or_b32 s6, s4, s5
	s_cmp_eq_u32 s6, 0
	s_cbranch_scc1 .Lna_endcompute
	s_sub_u32 s2, s1, s46
	s_add_u32 s2, s2, 7
	s_cmp_eq_u32 s4, 1
	s_cselect_b32 s6, s2, 15
	s_lshl_b32 s6, s6, 7
	s_add_u32 s78, s6, 0x11800
	s_sub_u32 s2, s2, 1
	s_cmp_eq_u32 s5, 1
	s_cselect_b32 s6, s2, 15
	s_lshl_b32 s6, s6, 7
	s_add_u32 s79, s6, 0x11800
	v_add_u32_e32 v232, s66, v198
	v_add_u32_e32 v233, s66, v200
	ds_read_b128 v[112:115], v232 offset:0
	ds_read_b128 v[116:119], v232 offset:4352
	ds_read_b128 v[120:123], v232 offset:64
	ds_read_b128 v[124:127], v232 offset:4416
	s_waitcnt lgkmcnt(2)
	v_mfma_f32_16x16x32_bf16 v[144:147], v[112:115], v[64:67], 0
	v_mfma_f32_16x16x32_bf16 v[148:151], v[116:119], v[64:67], 0
	v_mfma_f32_16x16x32_bf16 v[152:155], v[112:115], v[80:83], 0
	v_mfma_f32_16x16x32_bf16 v[156:159], v[116:119], v[80:83], 0
	ds_read_b128 v[112:115], v232 offset:128
	ds_read_b128 v[116:119], v232 offset:4480
	v_add_u32_e32 v160, s78, v202
	ds_read_b32 v160, v160
	v_add_u32_e32 v161, s78, v203
	ds_read_b32 v161, v161
	v_add_u32_e32 v162, s78, v204
	ds_read_b32 v162, v162
	v_add_u32_e32 v163, s78, v205
	ds_read_b32 v163, v163
	v_add_u32_e32 v164, s78, v206
	ds_read_b32 v164, v164
	v_add_u32_e32 v165, s78, v207
	ds_read_b32 v165, v165
	v_add_u32_e32 v166, s78, v208
	ds_read_b32 v166, v166
	v_add_u32_e32 v167, s78, v209
	ds_read_b32 v167, v167
	s_waitcnt lgkmcnt(10)
	v_mfma_f32_16x16x32_bf16 v[144:147], v[120:123], v[68:71], v[144:147]
	v_mfma_f32_16x16x32_bf16 v[148:151], v[124:127], v[68:71], v[148:151]
	v_mfma_f32_16x16x32_bf16 v[152:155], v[120:123], v[84:87], v[152:155]
	v_mfma_f32_16x16x32_bf16 v[156:159], v[124:127], v[84:87], v[156:159]
	ds_read_b128 v[120:123], v232 offset:192
	ds_read_b128 v[124:127], v232 offset:4544
	s_waitcnt lgkmcnt(10)
	v_mfma_f32_16x16x32_bf16 v[144:147], v[112:115], v[72:75], v[144:147]
	v_mfma_f32_16x16x32_bf16 v[148:151], v[116:119], v[72:75], v[148:151]
	v_mfma_f32_16x16x32_bf16 v[152:155], v[112:115], v[88:91], v[152:155]
	v_mfma_f32_16x16x32_bf16 v[156:159], v[116:119], v[88:91], v[156:159]
	s_waitcnt lgkmcnt(0)
	v_mfma_f32_16x16x32_bf16 v[144:147], v[120:123], v[76:79], v[144:147]
	v_mfma_f32_16x16x32_bf16 v[148:151], v[124:127], v[76:79], v[148:151]
	v_mfma_f32_16x16x32_bf16 v[152:155], v[120:123], v[92:95], v[152:155]
	v_mfma_f32_16x16x32_bf16 v[156:159], v[124:127], v[92:95], v[156:159]
	v_add_u32_e32 v179, s79, v202
	ds_read_b32 v179, v179
	v_add_u32_e32 v180, s79, v203
	ds_read_b32 v180, v180
	v_add_u32_e32 v181, s79, v204
	ds_read_b32 v181, v181
	v_add_u32_e32 v182, s79, v205
	ds_read_b32 v182, v182
	v_add_u32_e32 v183, s79, v206
	ds_read_b32 v183, v183
	v_add_u32_e32 v184, s79, v207
	ds_read_b32 v184, v184
	v_add_u32_e32 v185, s79, v208
	ds_read_b32 v185, v185
	v_add_u32_e32 v186, s79, v209
	ds_read_b32 v186, v186
	ds_read_b64_tr_b16 v[112:113], v233 offset:0
	ds_read_b64_tr_b16 v[114:115], v233 offset:4608
	ds_read_b64_tr_b16 v[116:117], v233 offset:32
	ds_read_b64_tr_b16 v[118:119], v233 offset:4640
	ds_read_b64_tr_b16 v[120:121], v233 offset:64
	ds_read_b64_tr_b16 v[122:123], v233 offset:4672
	s_waitcnt lgkmcnt(6)
	v_fma_f32 v160, v144, s53, v160
	v_fma_f32 v161, v145, s53, v161
	v_fma_f32 v162, v146, s53, v162
	v_fma_f32 v163, v147, s53, v163
	v_fma_f32 v164, v148, s53, v164
	v_fma_f32 v165, v149, s53, v165
	v_fma_f32 v166, v150, s53, v166
	v_fma_f32 v167, v151, s53, v167
	v_max3_f32 v224, v160, v161, v162
	v_max3_f32 v224, v224, v163, v164
	v_max3_f32 v224, v224, v165, v166
	v_max_f32_e32 v224, v224, v167
	v_cmp_gt_f32_e32 vcc, v224, v219
	s_cbranch_vccnz .Lna_rare_L_b0
.Lna_cont_L_b0:
	v_sub_f32_e32 v160, v160, v218
	v_sub_f32_e32 v161, v161, v218
	v_sub_f32_e32 v162, v162, v218
	v_sub_f32_e32 v163, v163, v218
	v_sub_f32_e32 v164, v164, v218
	v_sub_f32_e32 v165, v165, v218
	v_sub_f32_e32 v166, v166, v218
	v_sub_f32_e32 v167, v167, v218
	v_exp_f32_e32 v160, v160
	v_exp_f32_e32 v161, v161
	v_exp_f32_e32 v162, v162
	v_exp_f32_e32 v163, v163
	v_exp_f32_e32 v164, v164
	v_exp_f32_e32 v165, v165
	v_exp_f32_e32 v166, v166
	v_exp_f32_e32 v167, v167
	v_add_f32_e32 v224, v160, v161
	v_add_f32_e32 v225, v162, v163
	v_add_f32_e32 v226, v164, v165
	v_add_f32_e32 v227, v166, v167
	v_add_f32_e32 v224, v224, v225
	v_add_f32_e32 v226, v226, v227
	v_add_f32_e32 v224, v224, v226
	v_add_f32_e32 v220, v220, v224
	v_cvt_pk_bf16_f32 v168, v160, v161
	v_cvt_pk_bf16_f32 v169, v162, v163
	v_cvt_pk_bf16_f32 v170, v164, v165
	v_cvt_pk_bf16_f32 v171, v166, v167
	v_fma_f32 v179, v152, s53, v179
	v_fma_f32 v180, v153, s53, v180
	v_fma_f32 v181, v154, s53, v181
	v_fma_f32 v182, v155, s53, v182
	v_fma_f32 v183, v156, s53, v183
	v_fma_f32 v184, v157, s53, v184
	v_fma_f32 v185, v158, s53, v185
	v_fma_f32 v186, v159, s53, v186
	v_max3_f32 v224, v179, v180, v181
	v_max3_f32 v224, v224, v182, v183
	v_max3_f32 v224, v224, v184, v185
	v_max_f32_e32 v224, v224, v186
	v_cmp_gt_f32_e32 vcc, v224, v222
	s_cbranch_vccnz .Lna_rare_L_b1
.Lna_cont_L_b1:
	v_sub_f32_e32 v179, v179, v221
	v_sub_f32_e32 v180, v180, v221
	v_sub_f32_e32 v181, v181, v221
	v_sub_f32_e32 v182, v182, v221
	v_sub_f32_e32 v183, v183, v221
	v_sub_f32_e32 v184, v184, v221
	v_sub_f32_e32 v185, v185, v221
	v_sub_f32_e32 v186, v186, v221
	v_exp_f32_e32 v179, v179
	v_exp_f32_e32 v180, v180
	v_exp_f32_e32 v181, v181
	v_exp_f32_e32 v182, v182
	v_exp_f32_e32 v183, v183
	v_exp_f32_e32 v184, v184
	v_exp_f32_e32 v185, v185
	v_exp_f32_e32 v186, v186
	v_add_f32_e32 v224, v179, v180
	v_add_f32_e32 v225, v181, v182
	v_add_f32_e32 v226, v183, v184
	v_add_f32_e32 v227, v185, v186
	v_add_f32_e32 v224, v224, v225
	v_add_f32_e32 v226, v226, v227
	v_add_f32_e32 v224, v224, v226
	v_add_f32_e32 v223, v223, v224
	v_cvt_pk_bf16_f32 v188, v179, v180
	v_cvt_pk_bf16_f32 v189, v181, v182
	v_cvt_pk_bf16_f32 v190, v183, v184
	v_cvt_pk_bf16_f32 v191, v185, v186
	s_waitcnt lgkmcnt(4)
	v_mfma_f32_16x16x32_bf16 v[0:3], v[112:115], v[168:171], v[0:3]
	v_mfma_f32_16x16x32_bf16 v[32:35], v[112:115], v[188:191], v[32:35]
	ds_read_b64_tr_b16 v[124:125], v233 offset:96
	ds_read_b64_tr_b16 v[126:127], v233 offset:4704
	s_waitcnt lgkmcnt(4)
	v_mfma_f32_16x16x32_bf16 v[4:7], v[116:119], v[168:171], v[4:7]
	v_mfma_f32_16x16x32_bf16 v[36:39], v[116:119], v[188:191], v[36:39]
	ds_read_b64_tr_b16 v[112:113], v233 offset:128
	ds_read_b64_tr_b16 v[114:115], v233 offset:4736
	s_waitcnt lgkmcnt(4)
	v_mfma_f32_16x16x32_bf16 v[8:11], v[120:123], v[168:171], v[8:11]
	v_mfma_f32_16x16x32_bf16 v[40:43], v[120:123], v[188:191], v[40:43]
	ds_read_b64_tr_b16 v[116:117], v233 offset:160
	ds_read_b64_tr_b16 v[118:119], v233 offset:4768
	s_waitcnt lgkmcnt(4)
	v_mfma_f32_16x16x32_bf16 v[12:15], v[124:127], v[168:171], v[12:15]
	v_mfma_f32_16x16x32_bf16 v[44:47], v[124:127], v[188:191], v[44:47]
	ds_read_b64_tr_b16 v[120:121], v233 offset:192
	ds_read_b64_tr_b16 v[122:123], v233 offset:4800
	s_waitcnt lgkmcnt(4)
	v_mfma_f32_16x16x32_bf16 v[16:19], v[112:115], v[168:171], v[16:19]
	v_mfma_f32_16x16x32_bf16 v[48:51], v[112:115], v[188:191], v[48:51]
	ds_read_b64_tr_b16 v[124:125], v233 offset:224
	ds_read_b64_tr_b16 v[126:127], v233 offset:4832
	s_waitcnt lgkmcnt(4)
	v_mfma_f32_16x16x32_bf16 v[20:23], v[116:119], v[168:171], v[20:23]
	v_mfma_f32_16x16x32_bf16 v[52:55], v[116:119], v[188:191], v[52:55]
	s_waitcnt lgkmcnt(2)
	v_mfma_f32_16x16x32_bf16 v[24:27], v[120:123], v[168:171], v[24:27]
	v_mfma_f32_16x16x32_bf16 v[56:59], v[120:123], v[188:191], v[56:59]
	s_waitcnt lgkmcnt(0)
	v_mfma_f32_16x16x32_bf16 v[28:31], v[124:127], v[168:171], v[28:31]
	v_mfma_f32_16x16x32_bf16 v[60:63], v[124:127], v[188:191], v[60:63]
	s_branch .Lna_endcompute
.Lna_ctx:
	v_add_u32_e32 v232, s66, v199
	v_add_u32_e32 v233, s66, v201
	s_mov_b32 s90, 0
.Lna_ctx_grp:
	ds_read_b128 v[112:115], v232 offset:0
	ds_read_b128 v[116:119], v232 offset:4352
	ds_read_b128 v[120:123], v232 offset:64
	ds_read_b128 v[124:127], v232 offset:4416
	s_waitcnt lgkmcnt(2)
	v_mfma_f32_16x16x32_bf16 v[144:147], v[112:115], v[64:67], 0
	v_mfma_f32_16x16x32_bf16 v[148:151], v[116:119], v[64:67], 0
	v_mfma_f32_16x16x32_bf16 v[152:155], v[112:115], v[80:83], 0
	v_mfma_f32_16x16x32_bf16 v[156:159], v[116:119], v[80:83], 0
	ds_read_b128 v[112:115], v232 offset:128
	ds_read_b128 v[116:119], v232 offset:4480
	s_waitcnt lgkmcnt(2)
	v_mfma_f32_16x16x32_bf16 v[144:147], v[120:123], v[68:71], v[144:147]
	v_mfma_f32_16x16x32_bf16 v[148:151], v[124:127], v[68:71], v[148:151]
	v_mfma_f32_16x16x32_bf16 v[152:155], v[120:123], v[84:87], v[152:155]
	v_mfma_f32_16x16x32_bf16 v[156:159], v[124:127], v[84:87], v[156:159]
	ds_read_b128 v[120:123], v232 offset:192
	ds_read_b128 v[124:127], v232 offset:4544
	s_waitcnt lgkmcnt(2)
	v_mfma_f32_16x16x32_bf16 v[144:147], v[112:115], v[72:75], v[144:147]
	v_mfma_f32_16x16x32_bf16 v[148:151], v[116:119], v[72:75], v[148:151]
	v_mfma_f32_16x16x32_bf16 v[152:155], v[112:115], v[88:91], v[152:155]
	v_mfma_f32_16x16x32_bf16 v[156:159], v[116:119], v[88:91], v[156:159]
	s_waitcnt lgkmcnt(0)
	v_mfma_f32_16x16x32_bf16 v[144:147], v[120:123], v[76:79], v[144:147]
	v_mfma_f32_16x16x32_bf16 v[148:151], v[124:127], v[76:79], v[148:151]
	v_mfma_f32_16x16x32_bf16 v[152:155], v[120:123], v[92:95], v[152:155]
	v_mfma_f32_16x16x32_bf16 v[156:159], v[124:127], v[92:95], v[156:159]
	ds_read_b64_tr_b16 v[112:113], v233 offset:0
	ds_read_b64_tr_b16 v[114:115], v233 offset:4608
	ds_read_b64_tr_b16 v[116:117], v233 offset:32
	ds_read_b64_tr_b16 v[118:119], v233 offset:4640
	ds_read_b64_tr_b16 v[120:121], v233 offset:64
	ds_read_b64_tr_b16 v[122:123], v233 offset:4672
	s_nop 1
	v_fma_f32 v160, v144, s53, -v218
	v_fma_f32 v161, v145, s53, -v218
	v_fma_f32 v162, v146, s53, -v218
	v_fma_f32 v163, v147, s53, -v218
	v_fma_f32 v164, v148, s53, -v218
	v_fma_f32 v165, v149, s53, -v218
	v_fma_f32 v166, v150, s53, -v218
	v_fma_f32 v167, v151, s53, -v218
	v_max3_f32 v224, v160, v161, v162
	v_max3_f32 v224, v224, v163, v164
	v_max3_f32 v224, v224, v165, v166
	v_max_f32_e32 v224, v224, v167
	v_cmp_lt_f32_e32 vcc, 0x41000000, v224
	s_cbranch_vccnz .Lna_rare_C_b0
.Lna_cont_C_b0:
	v_exp_f32_e32 v160, v160
	v_exp_f32_e32 v161, v161
	v_exp_f32_e32 v162, v162
	v_exp_f32_e32 v163, v163
	v_exp_f32_e32 v164, v164
	v_exp_f32_e32 v165, v165
	v_exp_f32_e32 v166, v166
	v_exp_f32_e32 v167, v167
	v_add_f32_e32 v224, v160, v161
	v_add_f32_e32 v225, v162, v163
	v_add_f32_e32 v226, v164, v165
	v_add_f32_e32 v227, v166, v167
	v_add_f32_e32 v224, v224, v225
	v_add_f32_e32 v226, v226, v227
	v_add_f32_e32 v224, v224, v226
	v_add_f32_e32 v220, v220, v224
	v_cvt_pk_bf16_f32 v168, v160, v161
	v_cvt_pk_bf16_f32 v169, v162, v163
	v_cvt_pk_bf16_f32 v170, v164, v165
	v_cvt_pk_bf16_f32 v171, v166, v167
	v_fma_f32 v179, v152, s53, -v221
	v_fma_f32 v180, v153, s53, -v221
	v_fma_f32 v181, v154, s53, -v221
	v_fma_f32 v182, v155, s53, -v221
	v_fma_f32 v183, v156, s53, -v221
	v_fma_f32 v184, v157, s53, -v221
	v_fma_f32 v185, v158, s53, -v221
	v_fma_f32 v186, v159, s53, -v221
	v_max3_f32 v224, v179, v180, v181
	v_max3_f32 v224, v224, v182, v183
	v_max3_f32 v224, v224, v184, v185
	v_max_f32_e32 v224, v224, v186
	v_cmp_lt_f32_e32 vcc, 0x41000000, v224
	s_cbranch_vccnz .Lna_rare_C_b1
.Lna_cont_C_b1:
	v_exp_f32_e32 v179, v179
	v_exp_f32_e32 v180, v180
	v_exp_f32_e32 v181, v181
	v_exp_f32_e32 v182, v182
	v_exp_f32_e32 v183, v183
	v_exp_f32_e32 v184, v184
	v_exp_f32_e32 v185, v185
	v_exp_f32_e32 v186, v186
	v_add_f32_e32 v224, v179, v180
	v_add_f32_e32 v225, v181, v182
	v_add_f32_e32 v226, v183, v184
	v_add_f32_e32 v227, v185, v186
	v_add_f32_e32 v224, v224, v225
	v_add_f32_e32 v226, v226, v227
	v_add_f32_e32 v224, v224, v226
	v_add_f32_e32 v223, v223, v224
	v_cvt_pk_bf16_f32 v188, v179, v180
	v_cvt_pk_bf16_f32 v189, v181, v182
	v_cvt_pk_bf16_f32 v190, v183, v184
	v_cvt_pk_bf16_f32 v191, v185, v186
	s_waitcnt lgkmcnt(4)
	v_mfma_f32_16x16x32_bf16 v[0:3], v[112:115], v[168:171], v[0:3]
	v_mfma_f32_16x16x32_bf16 v[32:35], v[112:115], v[188:191], v[32:35]
	ds_read_b64_tr_b16 v[124:125], v233 offset:96
	ds_read_b64_tr_b16 v[126:127], v233 offset:4704
	s_waitcnt lgkmcnt(4)
	v_mfma_f32_16x16x32_bf16 v[4:7], v[116:119], v[168:171], v[4:7]
	v_mfma_f32_16x16x32_bf16 v[36:39], v[116:119], v[188:191], v[36:39]
	ds_read_b64_tr_b16 v[112:113], v233 offset:128
	ds_read_b64_tr_b16 v[114:115], v233 offset:4736
	s_waitcnt lgkmcnt(4)
	v_mfma_f32_16x16x32_bf16 v[8:11], v[120:123], v[168:171], v[8:11]
	v_mfma_f32_16x16x32_bf16 v[40:43], v[120:123], v[188:191], v[40:43]
	ds_read_b64_tr_b16 v[116:117], v233 offset:160
	ds_read_b64_tr_b16 v[118:119], v233 offset:4768
	s_waitcnt lgkmcnt(4)
	v_mfma_f32_16x16x32_bf16 v[12:15], v[124:127], v[168:171], v[12:15]
	v_mfma_f32_16x16x32_bf16 v[44:47], v[124:127], v[188:191], v[44:47]
	ds_read_b64_tr_b16 v[120:121], v233 offset:192
	ds_read_b64_tr_b16 v[122:123], v233 offset:4800
	s_waitcnt lgkmcnt(4)
	v_mfma_f32_16x16x32_bf16 v[16:19], v[112:115], v[168:171], v[16:19]
	v_mfma_f32_16x16x32_bf16 v[48:51], v[112:115], v[188:191], v[48:51]
	ds_read_b64_tr_b16 v[124:125], v233 offset:224
	ds_read_b64_tr_b16 v[126:127], v233 offset:4832
	s_waitcnt lgkmcnt(4)
	v_mfma_f32_16x16x32_bf16 v[20:23], v[116:119], v[168:171], v[20:23]
	v_mfma_f32_16x16x32_bf16 v[52:55], v[116:119], v[188:191], v[52:55]
	s_waitcnt lgkmcnt(2)
	v_mfma_f32_16x16x32_bf16 v[24:27], v[120:123], v[168:171], v[24:27]
	v_mfma_f32_16x16x32_bf16 v[56:59], v[120:123], v[188:191], v[56:59]
	s_waitcnt lgkmcnt(0)
	v_mfma_f32_16x16x32_bf16 v[28:31], v[124:127], v[168:171], v[28:31]
	v_mfma_f32_16x16x32_bf16 v[60:63], v[124:127], v[188:191], v[60:63]
	v_add_u32_e32 v232, 0x2200, v232
	v_add_u32_e32 v233, 0x2400, v233
	s_add_u32 s90, s90, 1
	s_cmp_lt_u32 s90, 2
	s_cbranch_scc1 .Lna_ctx_grp
.Lna_endcompute:
	s_cmp_eq_u32 s67, 0
	s_cbranch_scc1 .Lna_nostore
	s_sub_u32 s1, 0x8c00, s66
	v_add_u32_e32 v234, s1, v196
	v_add_u32_e32 v235, s1, v197
	s_cmp_eq_u32 s14, 0
	s_cbranch_scc1 .Lna_w0
	s_waitcnt vmcnt(4)
	s_branch .Lna_w1

.Lna_w1:
	s_bitcmp1_b32 s52, 0
	s_cbranch_scc1 .Lna_st_odd
	ds_write_b128 v234, v[128:131]
	ds_write_b128 v235, v[132:135]
	ds_write_b128 v234, v[136:139] offset:8704
	ds_write_b128 v235, v[140:143] offset:9216
	s_branch .Lna_nostore
.Lna_st_odd:
	ds_write_b128 v234, v[96:99]
	ds_write_b128 v235, v[100:103]
	ds_write_b128 v234, v[104:107] offset:8704
	ds_write_b128 v235, v[108:111] offset:9216
.Lna_nostore:
	s_waitcnt lgkmcnt(0)
	s_barrier
	s_sub_u32 s66, 0x8c00, s66
	s_add_u32 s52, s52, 1
	s_cmp_lt_u32 s52, s51
	s_cbranch_scc1 .Lna_it
	s_lshl_b32 s6, s43, 8
	s_lshl_b32 s7, s8, 15
	s_add_u32 s7, s7, s6
	s_add_u32 s7, s7, 0x6000
	s_add_u32 s72, s26, s7
	s_addc_u32 s73, s27, 0
	s_lshl_b32 s7, s8, 13
	s_add_u32 s7, s7, s6
	s_add_u32 s12, s28, s7
	s_addc_u32 s13, s29, 0
	global_load_dwordx2 v[112:113], v211, s[72:73] offset:0
	global_load_dwordx2 v[114:115], v211, s[72:73] offset:32
	global_load_dwordx2 v[116:117], v211, s[72:73] offset:64
	global_load_dwordx2 v[118:119], v211, s[72:73] offset:96
	global_load_dwordx2 v[120:121], v211, s[72:73] offset:128
	global_load_dwordx2 v[122:123], v211, s[72:73] offset:160
	global_load_dwordx2 v[124:125], v211, s[72:73] offset:192
	global_load_dwordx2 v[126:127], v211, s[72:73] offset:224
	s_lshl_b32 s7, s9, 15
	s_add_u32 s7, s7, s6
	s_add_u32 s7, s7, 0x6000
	s_add_u32 s16, s26, s7
	s_addc_u32 s17, s27, 0
	s_lshl_b32 s7, s9, 13
	s_add_u32 s7, s7, s6
	s_add_u32 s30, s28, s7
	s_addc_u32 s31, s29, 0
	global_load_dwordx2 v[144:145], v211, s[16:17] offset:0
	global_load_dwordx2 v[146:147], v211, s[16:17] offset:32
	global_load_dwordx2 v[148:149], v211, s[16:17] offset:64
	global_load_dwordx2 v[150:151], v211, s[16:17] offset:96
	global_load_dwordx2 v[152:153], v211, s[16:17] offset:128
	global_load_dwordx2 v[154:155], v211, s[16:17] offset:160
	global_load_dwordx2 v[156:157], v211, s[16:17] offset:192
	global_load_dwordx2 v[158:159], v211, s[16:17] offset:224
	s_add_u32 s15, s40, s94
	s_cmp_lt_u32 s15, s41
	s_cselect_b32 s40, s15, s40
	s_cmp_ge_u32 s40, 0x400
	s_cbranch_scc1 .Lna_dec_ctx_1
	s_mov_b32 s45, 0
	s_cmp_eq_u32 s94, 0x100
	s_cbranch_scc0 .Lna_dec_gen_1
	s_lshr_b32 s1, s40, 8
	s_and_b32 s2, s40, 0xff
	s_lshl_b32 s1, s1, 5
	s_and_b32 s4, s2, 7
	s_lshl_b32 s4, s4, 2
	s_add_u32 s1, s1, s4
	s_lshr_b32 s4, s2, 6
	s_add_u32 s1, s1, s4
	s_bfe_u32 s44, s2, 0x30003
	s_branch .Lna_dec_l2_1

.Lna_tb_done4:
	s_lshl_b32 s1, s1, 15
	s_lshl_b32 s2, s43, 8
	s_add_u32 s1, s1, s2
	s_add_u32 s1, s1, 0x2000
	s_add_u32 s54, s26, s1
	s_addc_u32 s55, s27, 0
	s_add_u32 s56, s54, 0x2000
	s_addc_u32 s57, s55, 0
	global_load_dwordx4 v[128:131], v194, s[54:55]
	global_load_dwordx4 v[132:135], v194, s[56:57]
	global_load_dwordx4 v[136:139], v195, s[54:55]
	global_load_dwordx4 v[140:143], v195, s[56:57]
	s_mov_b32 s4, 0xbfb8aa3b
	s_mov_b32 s5, 0xbfb8aa3b
	ds_bpermute_b32 v224, v215, v220
	s_waitcnt lgkmcnt(0)
	v_add_f32_e32 v220, v220, v224
	ds_bpermute_b32 v224, v216, v220
	s_waitcnt lgkmcnt(0)
	v_add_f32_e32 v224, v220, v224
	v_mov_b32_e32 v225, v224
	s_waitcnt vmcnt(25)
	v_lshlrev_b32_e32 v226, 16, v112
	v_and_b32_e32 v227, 0xffff0000, v112
	v_lshlrev_b32_e32 v228, 16, v113
	v_and_b32_e32 v229, 0xffff0000, v113
	v_pk_mul_f32 v[230:231], v[226:227], s[4:5]
	v_pk_mul_f32 v[160:161], v[228:229], s[4:5]
	v_exp_f32_e32 v230, v230
	v_exp_f32_e32 v231, v231
	v_exp_f32_e32 v160, v160
	v_exp_f32_e32 v161, v161
	v_pk_mul_f32 v[0:1], v[0:1], v[226:227]
	v_pk_mul_f32 v[2:3], v[2:3], v[228:229]
	v_pk_fma_f32 v[230:231], v[230:231], v[224:225], v[224:225]
	v_pk_fma_f32 v[160:161], v[160:161], v[224:225], v[224:225]
	v_rcp_f32_e32 v230, v230
	v_rcp_f32_e32 v231, v231
	v_rcp_f32_e32 v160, v160
	v_rcp_f32_e32 v161, v161
	s_nop 0
	v_pk_mul_f32 v[0:1], v[0:1], v[230:231]
	v_pk_mul_f32 v[2:3], v[2:3], v[160:161]
	v_cvt_pk_bf16_f32 v0, v0, v1
	v_cvt_pk_bf16_f32 v1, v2, v3
	global_store_dwordx2 v212, v[0:1], s[12:13] offset:0
	v_lshlrev_b32_e32 v226, 16, v114
	v_and_b32_e32 v227, 0xffff0000, v114
	v_lshlrev_b32_e32 v228, 16, v115
	v_and_b32_e32 v229, 0xffff0000, v115
	v_pk_mul_f32 v[230:231], v[226:227], s[4:5]
	v_pk_mul_f32 v[160:161], v[228:229], s[4:5]
	v_exp_f32_e32 v230, v230
	v_exp_f32_e32 v231, v231
	v_exp_f32_e32 v160, v160
	v_exp_f32_e32 v161, v161
	v_pk_mul_f32 v[4:5], v[4:5], v[226:227]
	v_pk_mul_f32 v[6:7], v[6:7], v[228:229]
	v_pk_fma_f32 v[230:231], v[230:231], v[224:225], v[224:225]
	v_pk_fma_f32 v[160:161], v[160:161], v[224:225], v[224:225]
	v_rcp_f32_e32 v230, v230
	v_rcp_f32_e32 v231, v231
	v_rcp_f32_e32 v160, v160
	v_rcp_f32_e32 v161, v161
	s_nop 0
	v_pk_mul_f32 v[4:5], v[4:5], v[230:231]
	v_pk_mul_f32 v[6:7], v[6:7], v[160:161]
	v_cvt_pk_bf16_f32 v4, v4, v5
	v_cvt_pk_bf16_f32 v5, v6, v7
	global_store_dwordx2 v212, v[4:5], s[12:13] offset:32
	v_lshlrev_b32_e32 v226, 16, v116
	v_and_b32_e32 v227, 0xffff0000, v116
	v_lshlrev_b32_e32 v228, 16, v117
	v_and_b32_e32 v229, 0xffff0000, v117
	v_pk_mul_f32 v[230:231], v[226:227], s[4:5]
	v_pk_mul_f32 v[160:161], v[228:229], s[4:5]
	v_exp_f32_e32 v230, v230
	v_exp_f32_e32 v231, v231
	v_exp_f32_e32 v160, v160
	v_exp_f32_e32 v161, v161
	v_pk_mul_f32 v[8:9], v[8:9], v[226:227]
	v_pk_mul_f32 v[10:11], v[10:11], v[228:229]
	v_pk_fma_f32 v[230:231], v[230:231], v[224:225], v[224:225]
	v_pk_fma_f32 v[160:161], v[160:161], v[224:225], v[224:225]
	v_rcp_f32_e32 v230, v230
	v_rcp_f32_e32 v231, v231
	v_rcp_f32_e32 v160, v160
	v_rcp_f32_e32 v161, v161
	s_nop 0
	v_pk_mul_f32 v[8:9], v[8:9], v[230:231]
	v_pk_mul_f32 v[10:11], v[10:11], v[160:161]
	v_cvt_pk_bf16_f32 v8, v8, v9
	v_cvt_pk_bf16_f32 v9, v10, v11
	global_store_dwordx2 v212, v[8:9], s[12:13] offset:64
	v_lshlrev_b32_e32 v226, 16, v118
	v_and_b32_e32 v227, 0xffff0000, v118
	v_lshlrev_b32_e32 v228, 16, v119
	v_and_b32_e32 v229, 0xffff0000, v119
	v_pk_mul_f32 v[230:231], v[226:227], s[4:5]
	v_pk_mul_f32 v[160:161], v[228:229], s[4:5]
	v_exp_f32_e32 v230, v230
	v_exp_f32_e32 v231, v231
	v_exp_f32_e32 v160, v160
	v_exp_f32_e32 v161, v161
	v_pk_mul_f32 v[12:13], v[12:13], v[226:227]
	v_pk_mul_f32 v[14:15], v[14:15], v[228:229]
	v_pk_fma_f32 v[230:231], v[230:231], v[224:225], v[224:225]
	v_pk_fma_f32 v[160:161], v[160:161], v[224:225], v[224:225]
	v_rcp_f32_e32 v230, v230
	v_rcp_f32_e32 v231, v231
	v_rcp_f32_e32 v160, v160
	v_rcp_f32_e32 v161, v161
	s_nop 0
	v_pk_mul_f32 v[12:13], v[12:13], v[230:231]
	v_pk_mul_f32 v[14:15], v[14:15], v[160:161]
	v_cvt_pk_bf16_f32 v12, v12, v13
	v_cvt_pk_bf16_f32 v13, v14, v15
	global_store_dwordx2 v212, v[12:13], s[12:13] offset:96
	v_lshlrev_b32_e32 v226, 16, v120
	v_and_b32_e32 v227, 0xffff0000, v120
	v_lshlrev_b32_e32 v228, 16, v121
	v_and_b32_e32 v229, 0xffff0000, v121
	v_pk_mul_f32 v[230:231], v[226:227], s[4:5]
	v_pk_mul_f32 v[160:161], v[228:229], s[4:5]
	v_exp_f32_e32 v230, v230
	v_exp_f32_e32 v231, v231
	v_exp_f32_e32 v160, v160
	v_exp_f32_e32 v161, v161
	v_pk_mul_f32 v[16:17], v[16:17], v[226:227]
	v_pk_mul_f32 v[18:19], v[18:19], v[228:229]
	v_pk_fma_f32 v[230:231], v[230:231], v[224:225], v[224:225]
	v_pk_fma_f32 v[160:161], v[160:161], v[224:225], v[224:225]
	v_rcp_f32_e32 v230, v230
	v_rcp_f32_e32 v231, v231
	v_rcp_f32_e32 v160, v160
	v_rcp_f32_e32 v161, v161
	s_nop 0
	v_pk_mul_f32 v[16:17], v[16:17], v[230:231]
	v_pk_mul_f32 v[18:19], v[18:19], v[160:161]
	v_cvt_pk_bf16_f32 v16, v16, v17
	v_cvt_pk_bf16_f32 v17, v18, v19
	global_store_dwordx2 v212, v[16:17], s[12:13] offset:128
	v_lshlrev_b32_e32 v226, 16, v122
	v_and_b32_e32 v227, 0xffff0000, v122
	v_lshlrev_b32_e32 v228, 16, v123
	v_and_b32_e32 v229, 0xffff0000, v123
	v_pk_mul_f32 v[230:231], v[226:227], s[4:5]
	v_pk_mul_f32 v[160:161], v[228:229], s[4:5]
	v_exp_f32_e32 v230, v230
	v_exp_f32_e32 v231, v231
	v_exp_f32_e32 v160, v160
	v_exp_f32_e32 v161, v161
	v_pk_mul_f32 v[20:21], v[20:21], v[226:227]
	v_pk_mul_f32 v[22:23], v[22:23], v[228:229]
	v_pk_fma_f32 v[230:231], v[230:231], v[224:225], v[224:225]
	v_pk_fma_f32 v[160:161], v[160:161], v[224:225], v[224:225]
	v_rcp_f32_e32 v230, v230
	v_rcp_f32_e32 v231, v231
	v_rcp_f32_e32 v160, v160
	v_rcp_f32_e32 v161, v161
	s_nop 0
	v_pk_mul_f32 v[20:21], v[20:21], v[230:231]
	v_pk_mul_f32 v[22:23], v[22:23], v[160:161]
	v_cvt_pk_bf16_f32 v20, v20, v21
	v_cvt_pk_bf16_f32 v21, v22, v23
	global_store_dwordx2 v212, v[20:21], s[12:13] offset:160
	v_lshlrev_b32_e32 v226, 16, v124
	v_and_b32_e32 v227, 0xffff0000, v124
	v_lshlrev_b32_e32 v228, 16, v125
	v_and_b32_e32 v229, 0xffff0000, v125
	v_pk_mul_f32 v[230:231], v[226:227], s[4:5]
	v_pk_mul_f32 v[160:161], v[228:229], s[4:5]
	v_exp_f32_e32 v230, v230
	v_exp_f32_e32 v231, v231
	v_exp_f32_e32 v160, v160
	v_exp_f32_e32 v161, v161
	v_pk_mul_f32 v[24:25], v[24:25], v[226:227]
	v_pk_mul_f32 v[26:27], v[26:27], v[228:229]
	v_pk_fma_f32 v[230:231], v[230:231], v[224:225], v[224:225]
	v_pk_fma_f32 v[160:161], v[160:161], v[224:225], v[224:225]
	v_rcp_f32_e32 v230, v230
	v_rcp_f32_e32 v231, v231
	v_rcp_f32_e32 v160, v160
	v_rcp_f32_e32 v161, v161
	s_nop 0
	v_pk_mul_f32 v[24:25], v[24:25], v[230:231]
	v_pk_mul_f32 v[26:27], v[26:27], v[160:161]
	v_cvt_pk_bf16_f32 v24, v24, v25
	v_cvt_pk_bf16_f32 v25, v26, v27
	global_store_dwordx2 v212, v[24:25], s[12:13] offset:192
	v_lshlrev_b32_e32 v226, 16, v126
	v_and_b32_e32 v227, 0xffff0000, v126
	v_lshlrev_b32_e32 v228, 16, v127
	v_and_b32_e32 v229, 0xffff0000, v127
	v_pk_mul_f32 v[230:231], v[226:227], s[4:5]
	v_pk_mul_f32 v[160:161], v[228:229], s[4:5]
	v_exp_f32_e32 v230, v230
	v_exp_f32_e32 v231, v231
	v_exp_f32_e32 v160, v160
	v_exp_f32_e32 v161, v161
	v_pk_mul_f32 v[28:29], v[28:29], v[226:227]
	v_pk_mul_f32 v[30:31], v[30:31], v[228:229]
	v_pk_fma_f32 v[230:231], v[230:231], v[224:225], v[224:225]
	v_pk_fma_f32 v[160:161], v[160:161], v[224:225], v[224:225]
	v_rcp_f32_e32 v230, v230
	v_rcp_f32_e32 v231, v231
	v_rcp_f32_e32 v160, v160
	v_rcp_f32_e32 v161, v161
	s_nop 0
	v_pk_mul_f32 v[28:29], v[28:29], v[230:231]
	v_pk_mul_f32 v[30:31], v[30:31], v[160:161]
	v_cvt_pk_bf16_f32 v28, v28, v29
	v_cvt_pk_bf16_f32 v29, v30, v31
	global_store_dwordx2 v212, v[28:29], s[12:13] offset:224
	ds_bpermute_b32 v224, v215, v223
	s_waitcnt lgkmcnt(0)
	v_add_f32_e32 v223, v223, v224
	ds_bpermute_b32 v224, v216, v223
	s_waitcnt lgkmcnt(0)
	v_add_f32_e32 v224, v223, v224
	v_mov_b32_e32 v225, v224
	s_waitcnt vmcnt(25)
	v_lshlrev_b32_e32 v226, 16, v144
	v_and_b32_e32 v227, 0xffff0000, v144
	v_lshlrev_b32_e32 v228, 16, v145
	v_and_b32_e32 v229, 0xffff0000, v145
	v_pk_mul_f32 v[230:231], v[226:227], s[4:5]
	v_pk_mul_f32 v[160:161], v[228:229], s[4:5]
	v_exp_f32_e32 v230, v230
	v_exp_f32_e32 v231, v231
	v_exp_f32_e32 v160, v160
	v_exp_f32_e32 v161, v161
	v_pk_mul_f32 v[32:33], v[32:33], v[226:227]
	v_pk_mul_f32 v[34:35], v[34:35], v[228:229]
	v_pk_fma_f32 v[230:231], v[230:231], v[224:225], v[224:225]
	v_pk_fma_f32 v[160:161], v[160:161], v[224:225], v[224:225]
	v_rcp_f32_e32 v230, v230
	v_rcp_f32_e32 v231, v231
	v_rcp_f32_e32 v160, v160
	v_rcp_f32_e32 v161, v161
	s_nop 0
	v_pk_mul_f32 v[32:33], v[32:33], v[230:231]
	v_pk_mul_f32 v[34:35], v[34:35], v[160:161]
	v_cvt_pk_bf16_f32 v32, v32, v33
	v_cvt_pk_bf16_f32 v33, v34, v35
	global_store_dwordx2 v212, v[32:33], s[30:31] offset:0
	v_lshlrev_b32_e32 v226, 16, v146
	v_and_b32_e32 v227, 0xffff0000, v146
	v_lshlrev_b32_e32 v228, 16, v147
	v_and_b32_e32 v229, 0xffff0000, v147
	v_pk_mul_f32 v[230:231], v[226:227], s[4:5]
	v_pk_mul_f32 v[160:161], v[228:229], s[4:5]
	v_exp_f32_e32 v230, v230
	v_exp_f32_e32 v231, v231
	v_exp_f32_e32 v160, v160
	v_exp_f32_e32 v161, v161
	v_pk_mul_f32 v[36:37], v[36:37], v[226:227]
	v_pk_mul_f32 v[38:39], v[38:39], v[228:229]
	v_pk_fma_f32 v[230:231], v[230:231], v[224:225], v[224:225]
	v_pk_fma_f32 v[160:161], v[160:161], v[224:225], v[224:225]
	v_rcp_f32_e32 v230, v230
	v_rcp_f32_e32 v231, v231
	v_rcp_f32_e32 v160, v160
	v_rcp_f32_e32 v161, v161
	s_nop 0
	v_pk_mul_f32 v[36:37], v[36:37], v[230:231]
	v_pk_mul_f32 v[38:39], v[38:39], v[160:161]
	v_cvt_pk_bf16_f32 v36, v36, v37
	v_cvt_pk_bf16_f32 v37, v38, v39
	global_store_dwordx2 v212, v[36:37], s[30:31] offset:32
	v_lshlrev_b32_e32 v226, 16, v148
	v_and_b32_e32 v227, 0xffff0000, v148
	v_lshlrev_b32_e32 v228, 16, v149
	v_and_b32_e32 v229, 0xffff0000, v149
	v_pk_mul_f32 v[230:231], v[226:227], s[4:5]
	v_pk_mul_f32 v[160:161], v[228:229], s[4:5]
	v_exp_f32_e32 v230, v230
	v_exp_f32_e32 v231, v231
	v_exp_f32_e32 v160, v160
	v_exp_f32_e32 v161, v161
	v_pk_mul_f32 v[40:41], v[40:41], v[226:227]
	v_pk_mul_f32 v[42:43], v[42:43], v[228:229]
	v_pk_fma_f32 v[230:231], v[230:231], v[224:225], v[224:225]
	v_pk_fma_f32 v[160:161], v[160:161], v[224:225], v[224:225]
	v_rcp_f32_e32 v230, v230
	v_rcp_f32_e32 v231, v231
	v_rcp_f32_e32 v160, v160
	v_rcp_f32_e32 v161, v161
	s_nop 0
	v_pk_mul_f32 v[40:41], v[40:41], v[230:231]
	v_pk_mul_f32 v[42:43], v[42:43], v[160:161]
	v_cvt_pk_bf16_f32 v40, v40, v41
	v_cvt_pk_bf16_f32 v41, v42, v43
	global_store_dwordx2 v212, v[40:41], s[30:31] offset:64
	v_lshlrev_b32_e32 v226, 16, v150
	v_and_b32_e32 v227, 0xffff0000, v150
	v_lshlrev_b32_e32 v228, 16, v151
	v_and_b32_e32 v229, 0xffff0000, v151
	v_pk_mul_f32 v[230:231], v[226:227], s[4:5]
	v_pk_mul_f32 v[160:161], v[228:229], s[4:5]
	v_exp_f32_e32 v230, v230
	v_exp_f32_e32 v231, v231
	v_exp_f32_e32 v160, v160
	v_exp_f32_e32 v161, v161
	v_pk_mul_f32 v[44:45], v[44:45], v[226:227]
	v_pk_mul_f32 v[46:47], v[46:47], v[228:229]
	v_pk_fma_f32 v[230:231], v[230:231], v[224:225], v[224:225]
	v_pk_fma_f32 v[160:161], v[160:161], v[224:225], v[224:225]
	v_rcp_f32_e32 v230, v230
	v_rcp_f32_e32 v231, v231
	v_rcp_f32_e32 v160, v160
	v_rcp_f32_e32 v161, v161
	s_nop 0
	v_pk_mul_f32 v[44:45], v[44:45], v[230:231]
	v_pk_mul_f32 v[46:47], v[46:47], v[160:161]
	v_cvt_pk_bf16_f32 v44, v44, v45
	v_cvt_pk_bf16_f32 v45, v46, v47
	global_store_dwordx2 v212, v[44:45], s[30:31] offset:96
	v_lshlrev_b32_e32 v226, 16, v152
	v_and_b32_e32 v227, 0xffff0000, v152
	v_lshlrev_b32_e32 v228, 16, v153
	v_and_b32_e32 v229, 0xffff0000, v153
	v_pk_mul_f32 v[230:231], v[226:227], s[4:5]
	v_pk_mul_f32 v[160:161], v[228:229], s[4:5]
	v_exp_f32_e32 v230, v230
	v_exp_f32_e32 v231, v231
	v_exp_f32_e32 v160, v160
	v_exp_f32_e32 v161, v161
	v_pk_mul_f32 v[48:49], v[48:49], v[226:227]
	v_pk_mul_f32 v[50:51], v[50:51], v[228:229]
	v_pk_fma_f32 v[230:231], v[230:231], v[224:225], v[224:225]
	v_pk_fma_f32 v[160:161], v[160:161], v[224:225], v[224:225]
	v_rcp_f32_e32 v230, v230
	v_rcp_f32_e32 v231, v231
	v_rcp_f32_e32 v160, v160
	v_rcp_f32_e32 v161, v161
	s_nop 0
	v_pk_mul_f32 v[48:49], v[48:49], v[230:231]
	v_pk_mul_f32 v[50:51], v[50:51], v[160:161]
	v_cvt_pk_bf16_f32 v48, v48, v49
	v_cvt_pk_bf16_f32 v49, v50, v51
	global_store_dwordx2 v212, v[48:49], s[30:31] offset:128
	v_lshlrev_b32_e32 v226, 16, v154
	v_and_b32_e32 v227, 0xffff0000, v154
	v_lshlrev_b32_e32 v228, 16, v155
	v_and_b32_e32 v229, 0xffff0000, v155
	v_pk_mul_f32 v[230:231], v[226:227], s[4:5]
	v_pk_mul_f32 v[160:161], v[228:229], s[4:5]
	v_exp_f32_e32 v230, v230
	v_exp_f32_e32 v231, v231
	v_exp_f32_e32 v160, v160
	v_exp_f32_e32 v161, v161
	v_pk_mul_f32 v[52:53], v[52:53], v[226:227]
	v_pk_mul_f32 v[54:55], v[54:55], v[228:229]
	v_pk_fma_f32 v[230:231], v[230:231], v[224:225], v[224:225]
	v_pk_fma_f32 v[160:161], v[160:161], v[224:225], v[224:225]
	v_rcp_f32_e32 v230, v230
	v_rcp_f32_e32 v231, v231
	v_rcp_f32_e32 v160, v160
	v_rcp_f32_e32 v161, v161
	s_nop 0
	v_pk_mul_f32 v[52:53], v[52:53], v[230:231]
	v_pk_mul_f32 v[54:55], v[54:55], v[160:161]
	v_cvt_pk_bf16_f32 v52, v52, v53
	v_cvt_pk_bf16_f32 v53, v54, v55
	global_store_dwordx2 v212, v[52:53], s[30:31] offset:160
	v_lshlrev_b32_e32 v226, 16, v156
	v_and_b32_e32 v227, 0xffff0000, v156
	v_lshlrev_b32_e32 v228, 16, v157
	v_and_b32_e32 v229, 0xffff0000, v157
	v_pk_mul_f32 v[230:231], v[226:227], s[4:5]
	v_pk_mul_f32 v[160:161], v[228:229], s[4:5]
	v_exp_f32_e32 v230, v230
	v_exp_f32_e32 v231, v231
	v_exp_f32_e32 v160, v160
	v_exp_f32_e32 v161, v161
	v_pk_mul_f32 v[56:57], v[56:57], v[226:227]
	v_pk_mul_f32 v[58:59], v[58:59], v[228:229]
	v_pk_fma_f32 v[230:231], v[230:231], v[224:225], v[224:225]
	v_pk_fma_f32 v[160:161], v[160:161], v[224:225], v[224:225]
	v_rcp_f32_e32 v230, v230
	v_rcp_f32_e32 v231, v231
	v_rcp_f32_e32 v160, v160
	v_rcp_f32_e32 v161, v161
	s_nop 0
	v_pk_mul_f32 v[56:57], v[56:57], v[230:231]
	v_pk_mul_f32 v[58:59], v[58:59], v[160:161]
	v_cvt_pk_bf16_f32 v56, v56, v57
	v_cvt_pk_bf16_f32 v57, v58, v59
	global_store_dwordx2 v212, v[56:57], s[30:31] offset:192
	v_lshlrev_b32_e32 v226, 16, v158
	v_and_b32_e32 v227, 0xffff0000, v158
	v_lshlrev_b32_e32 v228, 16, v159
	v_and_b32_e32 v229, 0xffff0000, v159
	v_pk_mul_f32 v[230:231], v[226:227], s[4:5]
	v_pk_mul_f32 v[160:161], v[228:229], s[4:5]
	v_exp_f32_e32 v230, v230
	v_exp_f32_e32 v231, v231
	v_exp_f32_e32 v160, v160
	v_exp_f32_e32 v161, v161
	v_pk_mul_f32 v[60:61], v[60:61], v[226:227]
	v_pk_mul_f32 v[62:63], v[62:63], v[228:229]
	v_pk_fma_f32 v[230:231], v[230:231], v[224:225], v[224:225]
	v_pk_fma_f32 v[160:161], v[160:161], v[224:225], v[224:225]
	v_rcp_f32_e32 v230, v230
	v_rcp_f32_e32 v231, v231
	v_rcp_f32_e32 v160, v160
	v_rcp_f32_e32 v161, v161
	s_nop 0
	v_pk_mul_f32 v[60:61], v[60:61], v[230:231]
	v_pk_mul_f32 v[62:63], v[62:63], v[160:161]
	v_cvt_pk_bf16_f32 v60, v60, v61
	v_cvt_pk_bf16_f32 v61, v62, v63
	global_store_dwordx2 v212, v[60:61], s[30:31] offset:224
	s_cmp_lt_u32 s15, s41
	s_cbranch_scc1 .Lna_unit_next
	s_branch .Lna_done
.Lna_rare_L_b0:
	ds_bpermute_b32 v225, v215, v224
	ds_bpermute_b32 v226, v216, v224
	ds_bpermute_b32 v227, v217, v224
	s_waitcnt lgkmcnt(0)
	v_max3_f32 v224, v224, v225, v226
	v_max_f32_e32 v224, v224, v227
	v_max_f32_e32 v225, v218, v224
	v_sub_f32_e32 v226, v218, v225
	v_exp_f32_e32 v226, v226
	v_mov_b32_e32 v218, v225
	v_add_f32_e32 v219, 0x41000000, v225
	v_mul_f32_e32 v220, v220, v226
	v_mul_f32_e32 v0, v0, v226
	v_mul_f32_e32 v1, v1, v226
	v_mul_f32_e32 v2, v2, v226
	v_mul_f32_e32 v3, v3, v226
	v_mul_f32_e32 v4, v4, v226
	v_mul_f32_e32 v5, v5, v226
	v_mul_f32_e32 v6, v6, v226
	v_mul_f32_e32 v7, v7, v226
	v_mul_f32_e32 v8, v8, v226
	v_mul_f32_e32 v9, v9, v226
	v_mul_f32_e32 v10, v10, v226
	v_mul_f32_e32 v11, v11, v226
	v_mul_f32_e32 v12, v12, v226
	v_mul_f32_e32 v13, v13, v226
	v_mul_f32_e32 v14, v14, v226
	v_mul_f32_e32 v15, v15, v226
	v_mul_f32_e32 v16, v16, v226
	v_mul_f32_e32 v17, v17, v226
	v_mul_f32_e32 v18, v18, v226
	v_mul_f32_e32 v19, v19, v226
	v_mul_f32_e32 v20, v20, v226
	v_mul_f32_e32 v21, v21, v226
	v_mul_f32_e32 v22, v22, v226
	v_mul_f32_e32 v23, v23, v226
	v_mul_f32_e32 v24, v24, v226
	v_mul_f32_e32 v25, v25, v226
	v_mul_f32_e32 v26, v26, v226
	v_mul_f32_e32 v27, v27, v226
	v_mul_f32_e32 v28, v28, v226
	v_mul_f32_e32 v29, v29, v226
	v_mul_f32_e32 v30, v30, v226
	v_mul_f32_e32 v31, v31, v226
	s_branch .Lna_cont_L_b0
.Lna_rare_L_b1:
	ds_bpermute_b32 v225, v215, v224
	ds_bpermute_b32 v226, v216, v224
	ds_bpermute_b32 v227, v217, v224
	s_waitcnt lgkmcnt(0)
	v_max3_f32 v224, v224, v225, v226
	v_max_f32_e32 v224, v224, v227
	v_max_f32_e32 v225, v221, v224
	v_sub_f32_e32 v226, v221, v225
	v_exp_f32_e32 v226, v226
	v_mov_b32_e32 v221, v225
	v_add_f32_e32 v222, 0x41000000, v225
	v_mul_f32_e32 v223, v223, v226
	v_mul_f32_e32 v32, v32, v226
	v_mul_f32_e32 v33, v33, v226
	v_mul_f32_e32 v34, v34, v226
	v_mul_f32_e32 v35, v35, v226
	v_mul_f32_e32 v36, v36, v226
	v_mul_f32_e32 v37, v37, v226
	v_mul_f32_e32 v38, v38, v226
	v_mul_f32_e32 v39, v39, v226
	v_mul_f32_e32 v40, v40, v226
	v_mul_f32_e32 v41, v41, v226
	v_mul_f32_e32 v42, v42, v226
	v_mul_f32_e32 v43, v43, v226
	v_mul_f32_e32 v44, v44, v226
	v_mul_f32_e32 v45, v45, v226
	v_mul_f32_e32 v46, v46, v226
	v_mul_f32_e32 v47, v47, v226
	v_mul_f32_e32 v48, v48, v226
	v_mul_f32_e32 v49, v49, v226
	v_mul_f32_e32 v50, v50, v226
	v_mul_f32_e32 v51, v51, v226
	v_mul_f32_e32 v52, v52, v226
	v_mul_f32_e32 v53, v53, v226
	v_mul_f32_e32 v54, v54, v226
	v_mul_f32_e32 v55, v55, v226
	v_mul_f32_e32 v56, v56, v226
	v_mul_f32_e32 v57, v57, v226
	v_mul_f32_e32 v58, v58, v226
	v_mul_f32_e32 v59, v59, v226
	v_mul_f32_e32 v60, v60, v226
	v_mul_f32_e32 v61, v61, v226
	v_mul_f32_e32 v62, v62, v226
	v_mul_f32_e32 v63, v63, v226
	s_branch .Lna_cont_L_b1
.Lna_rare_C_b0:
	v_mul_f32_e32 v160, s53, v144
	v_mul_f32_e32 v161, s53, v145
	v_mul_f32_e32 v162, s53, v146
	v_mul_f32_e32 v163, s53, v147
	v_mul_f32_e32 v164, s53, v148
	v_mul_f32_e32 v165, s53, v149
	v_mul_f32_e32 v166, s53, v150
	v_mul_f32_e32 v167, s53, v151
	v_max3_f32 v224, v160, v161, v162
	v_max3_f32 v224, v224, v163, v164
	v_max3_f32 v224, v224, v165, v166
	v_max_f32_e32 v224, v224, v167
	ds_bpermute_b32 v225, v215, v224
	ds_bpermute_b32 v226, v216, v224
	ds_bpermute_b32 v227, v217, v224
	s_waitcnt lgkmcnt(0)
	v_max3_f32 v224, v224, v225, v226
	v_max_f32_e32 v224, v224, v227
	v_max_f32_e32 v225, v218, v224
	v_sub_f32_e32 v226, v218, v225
	v_exp_f32_e32 v226, v226
	v_mov_b32_e32 v218, v225
	v_add_f32_e32 v219, 0x41000000, v225
	v_mul_f32_e32 v220, v220, v226
	v_mul_f32_e32 v0, v0, v226
	v_mul_f32_e32 v1, v1, v226
	v_mul_f32_e32 v2, v2, v226
	v_mul_f32_e32 v3, v3, v226
	v_mul_f32_e32 v4, v4, v226
	v_mul_f32_e32 v5, v5, v226
	v_mul_f32_e32 v6, v6, v226
	v_mul_f32_e32 v7, v7, v226
	v_mul_f32_e32 v8, v8, v226
	v_mul_f32_e32 v9, v9, v226
	v_mul_f32_e32 v10, v10, v226
	v_mul_f32_e32 v11, v11, v226
	v_mul_f32_e32 v12, v12, v226
	v_mul_f32_e32 v13, v13, v226
	v_mul_f32_e32 v14, v14, v226
	v_mul_f32_e32 v15, v15, v226
	v_mul_f32_e32 v16, v16, v226
	v_mul_f32_e32 v17, v17, v226
	v_mul_f32_e32 v18, v18, v226
	v_mul_f32_e32 v19, v19, v226
	v_mul_f32_e32 v20, v20, v226
	v_mul_f32_e32 v21, v21, v226
	v_mul_f32_e32 v22, v22, v226
	v_mul_f32_e32 v23, v23, v226
	v_mul_f32_e32 v24, v24, v226
	v_mul_f32_e32 v25, v25, v226
	v_mul_f32_e32 v26, v26, v226
	v_mul_f32_e32 v27, v27, v226
	v_mul_f32_e32 v28, v28, v226
	v_mul_f32_e32 v29, v29, v226
	v_mul_f32_e32 v30, v30, v226
	v_mul_f32_e32 v31, v31, v226
	v_sub_f32_e32 v160, v160, v218
	v_sub_f32_e32 v161, v161, v218
	v_sub_f32_e32 v162, v162, v218
	v_sub_f32_e32 v163, v163, v218
	v_sub_f32_e32 v164, v164, v218
	v_sub_f32_e32 v165, v165, v218
	v_sub_f32_e32 v166, v166, v218
	v_sub_f32_e32 v167, v167, v218
	s_branch .Lna_cont_C_b0
.Lna_rare_C_b1:
	v_mul_f32_e32 v179, s53, v152
	v_mul_f32_e32 v180, s53, v153
	v_mul_f32_e32 v181, s53, v154
	v_mul_f32_e32 v182, s53, v155
	v_mul_f32_e32 v183, s53, v156
	v_mul_f32_e32 v184, s53, v157
	v_mul_f32_e32 v185, s53, v158
	v_mul_f32_e32 v186, s53, v159
	v_max3_f32 v224, v179, v180, v181
	v_max3_f32 v224, v224, v182, v183
	v_max3_f32 v224, v224, v184, v185
	v_max_f32_e32 v224, v224, v186
	ds_bpermute_b32 v225, v215, v224
	ds_bpermute_b32 v226, v216, v224
	ds_bpermute_b32 v227, v217, v224
	s_waitcnt lgkmcnt(0)
	v_max3_f32 v224, v224, v225, v226
	v_max_f32_e32 v224, v224, v227
	v_max_f32_e32 v225, v221, v224
	v_sub_f32_e32 v226, v221, v225
	v_exp_f32_e32 v226, v226
	v_mov_b32_e32 v221, v225
	v_add_f32_e32 v222, 0x41000000, v225
	v_mul_f32_e32 v223, v223, v226
	v_mul_f32_e32 v32, v32, v226
	v_mul_f32_e32 v33, v33, v226
	v_mul_f32_e32 v34, v34, v226
	v_mul_f32_e32 v35, v35, v226
	v_mul_f32_e32 v36, v36, v226
	v_mul_f32_e32 v37, v37, v226
	v_mul_f32_e32 v38, v38, v226
	v_mul_f32_e32 v39, v39, v226
	v_mul_f32_e32 v40, v40, v226
	v_mul_f32_e32 v41, v41, v226
	v_mul_f32_e32 v42, v42, v226
	v_mul_f32_e32 v43, v43, v226
	v_mul_f32_e32 v44, v44, v226
	v_mul_f32_e32 v45, v45, v226
	v_mul_f32_e32 v46, v46, v226
	v_mul_f32_e32 v47, v47, v226
	v_mul_f32_e32 v48, v48, v226
	v_mul_f32_e32 v49, v49, v226
	v_mul_f32_e32 v50, v50, v226
	v_mul_f32_e32 v51, v51, v226
	v_mul_f32_e32 v52, v52, v226
	v_mul_f32_e32 v53, v53, v226
	v_mul_f32_e32 v54, v54, v226
	v_mul_f32_e32 v55, v55, v226
	v_mul_f32_e32 v56, v56, v226
	v_mul_f32_e32 v57, v57, v226
	v_mul_f32_e32 v58, v58, v226
	v_mul_f32_e32 v59, v59, v226
	v_mul_f32_e32 v60, v60, v226
	v_mul_f32_e32 v61, v61, v226
	v_mul_f32_e32 v62, v62, v226
	v_mul_f32_e32 v63, v63, v226
	v_sub_f32_e32 v179, v179, v221
	v_sub_f32_e32 v180, v180, v221
	v_sub_f32_e32 v181, v181, v221
	v_sub_f32_e32 v182, v182, v221
	v_sub_f32_e32 v183, v183, v221
	v_sub_f32_e32 v184, v184, v221
	v_sub_f32_e32 v185, v185, v221
	v_sub_f32_e32 v186, v186, v221
	s_branch .Lna_cont_C_b1
.Lna_done:
	s_waitcnt vmcnt(0)
.LBB0_330:
	v_readlane_b32 s44, v254, 47
	v_readlane_b32 s60, v254, 63
	v_readlane_b32 s64, v255, 1
	v_readlane_b32 s66, v255, 3
	v_readlane_b32 s72, v255, 5
	v_readlane_b32 s14, v255, 7
	v_readlane_b32 s28, v255, 9
	v_readlane_b32 s24, v253, 16
	s_mov_b64 s[6:7], 0
	v_readlane_b32 s45, v254, 48
	v_readlane_b32 s46, v254, 49
	v_readlane_b32 s47, v254, 50
	v_readlane_b32 s48, v254, 51
	v_readlane_b32 s49, v254, 52
	v_readlane_b32 s50, v254, 53
	v_readlane_b32 s51, v254, 54
	v_readlane_b32 s52, v254, 55
	v_readlane_b32 s53, v254, 56
	v_readlane_b32 s54, v254, 57
	v_readlane_b32 s55, v254, 58
	v_readlane_b32 s56, v254, 59
	v_readlane_b32 s57, v254, 60
	v_readlane_b32 s58, v254, 61
	v_readlane_b32 s59, v254, 62
	v_readlane_b32 s61, v255, 0
	v_readlane_b32 s65, v255, 2
	v_readlane_b32 s67, v255, 4
	v_readlane_b32 s73, v255, 6
	v_readlane_b32 s15, v255, 8
	v_readlane_b32 s29, v255, 10
	v_readlane_b32 s25, v253, 17
